# e15: out_proj tiles preload the gate vector and x row-block 0 before the K loop (tile 1 at phase start, tile 2 behind tile 1's stores) into VGPRs the loop never touches
# baseline (speedup 1.0000x reference)
; __device__ __forceinline__ f32x4 ld_nt(const float* p) { return __builtin_nontemporal_load((const f32x4*)p); }
; #define PG8_STAGE_A(bufoff, gbase) PG8_STAGE(bufoff, gbase, voffA, a64)
; #define PG8_STAGE_B(bufoff, bp, hb, tz) do { if (BMODE == 1 && (tz)) PG8_STAGE(bufoff, (bp) + (hb) * 4096, voffT, t64); else PG8_STAGE(bufoff, (bp) + (hb) * bhstep, voffB, b64); } while (0)
; template <class CF, class Epi, class Sched, bool ALIGN_EPI, bool SP2>
; __device__ __forceinline__ void gemm_phase(LAS unsigned char* lds, const char* gA, const char* gB, const Sched& S, const Epi& E, const char* gB2 = nullptr) {
;     ...
;     PG8_STAGE_B(PG8_SB(0, 0), cB, 0, false); PG8_STAGE_B(PG8_SB(0, 1), cB, 1, false); PG8_STAGE_A(PG8_SA(0, 0), cA); PG8_STAGE_A(PG8_SA(0, 1), cA + ahstep);
;     __device__ __forceinline__ void operator()(AccRef acc, const Unit& u, int wr, int wc, int fr, int fq) const {
;         int row0 = u.pm * 256 + wr * 64 + fr; asm volatile("" : "+v"(row0)); int col0 = u.pn * 256 + wc * 32 + 8 * fq; asm volatile("" : "+v"(col0));
;         const float* gate = mod + (size_t)(u.pm >= 32 ? 1 : 0) * 3 * D + 2 * D + col0;
;         f32x4 gv[2][2];
; #pragma unroll
;         for (int bj = 0; bj < 2; ++bj)
; #pragma unroll
;             for (int n = 0; n < 2; ++n) gv[bj][n] = *(const f32x4*)(gate + bj * HALF + n * 4);
; #pragma unroll
;         for (int ai = 0; ai < 2; ++ai)
; #pragma unroll
;             for (int mp = 0; mp < 2; ++mp) { f32x4 xv[2][2][2];
; #pragma unroll
;                 for (int mm = 0; mm < 2; ++mm)
; #pragma unroll
;                     for (int bj = 0; bj < 2; ++bj)
; #pragma unroll
;                         for (int n = 0; n < 2; ++n) xv[mm][bj][n] = ld_nt(x + (size_t)(row0 + ai * HALF + (mp * 2 + mm) * 16) * D + col0 + bj * HALF + n * 4);
.LBB0_1138:
	s_andn2_b64 vcc, exec, s[2:3]
	s_cbranch_vccnz .LBB0_1174
	v_and_b32_e32 v252, 15, v0
	v_lshrrev_b32_e32 v253, 8, v0
	v_lshl_or_b32 v252, v253, 6, v252
	v_bfe_u32 v253, v0, 6, 2
	v_bfe_u32 v251, v0, 4, 2
	v_lshlrev_b32_e32 v251, 3, v251
	v_lshl_or_b32 v253, v253, 5, v251
	v_lshl_add_u32 v250, s58, 8, v252
	v_lshl_or_b32 v251, s22, 8, v253
	v_readlane_b32 s98, v254, 2
	v_readlane_b32 s99, v254, 3
	v_lshlrev_b32_e32 v250, 13, v250
	v_lshlrev_b32_e32 v251, 2, v251
	s_cmp_gt_i32 s58, 31
	s_cselect_b32 vcc_lo, 0x6000, 0
	s_add_u32 s100, s50, vcc_lo
	s_addc_u32 s101, s51, 0
	s_add_u32 s100, s100, 0x104000
	s_addc_u32 s101, s101, 0
	v_add_u32_e32 v250, v250, v251
	s_nop 1
	global_load_dwordx4 v[218:221], v251, s[100:101]
	global_load_dwordx4 v[222:225], v251, s[100:101] offset:16
	global_load_dwordx4 v[226:229], v251, s[100:101] offset:512
	global_load_dwordx4 v[230:233], v251, s[100:101] offset:528
	global_load_dwordx4 v[234:237], v250, s[98:99] nt
	global_load_dwordx4 v[238:241], v250, s[98:99] offset:16 nt
	global_load_dwordx4 v[242:245], v250, s[98:99] offset:512 nt
	global_load_dwordx4 v[246:249], v250, s[98:99] offset:528 nt
	s_add_u32 s0, s50, 0x19800000
	s_addc_u32 s1, s51, 0
	s_add_u32 s33, s50, 0x1400000
	s_addc_u32 s64, s51, 0
	s_lshr_b32 s3, s18, 6
	s_ashr_i32 s59, s58, 31
	s_lshr_b32 s2, s18, 8
	s_lshl_b32 s65, s3, 10
	s_lshl_b64 s[4:5], s[58:59], 20
	v_lshlrev_b32_e32 v2, 4, v0
	v_and_b32_e32 v3, 32, v0
	v_lshrrev_b32_e32 v4, 3, v0
	v_bfe_u32 v1, v0, 2, 4
	s_add_u32 s20, s0, s4
	v_and_or_b32 v5, v4, 48, v1
	v_bitop3_b32 v6, v2, v3, 48 bitop3:0x6c
	v_and_b32_e32 v3, 32, v4
	v_lshrrev_b32_e32 v4, 1, v0
	v_lshrrev_b32_e32 v8, 5, v0
	v_bfe_u32 v9, v0, 2, 2
	s_addc_u32 s21, s1, s5
	s_ashr_i32 s23, s22, 31
	v_and_b32_e32 v7, 64, v0
	v_and_b32_e32 v4, 24, v4
	v_and_or_b32 v8, v8, 4, v9
	s_lshl_b64 s[4:5], s[22:23], 20
	v_or_b32_e32 v2, v6, v7
	v_or3_b32 v3, v8, v3, v4
	s_add_u32 s62, s33, s4
	v_lshl_or_b32 v162, v3, 12, v2
	s_addc_u32 s63, s64, s5
	v_mov_b32_e32 v163, 0
	s_add_i32 s66, s65, 0
	v_lshl_or_b32 v160, v5, 12, v2
	v_lshl_add_u64 v[2:3], s[62:63], 0, v[162:163]
	s_add_i32 m0, s66, 0x10000
	s_mov_b64 s[8:9], 0x40000
	global_load_lds_dwordx4 v162, s[62:63]
	v_lshl_add_u64 v[4:5], v[2:3], 0, s[8:9]
	s_add_i32 m0, s66, 0x12000
	s_mov_b64 s[10:11], 0x80000
	global_load_lds_dwordx4 v[4:5], off
	v_lshl_add_u64 v[4:5], v[2:3], 0, s[10:11]
	s_add_i32 m0, s66, 0x14000
	s_mov_b64 s[12:13], 0xc0000
	global_load_lds_dwordx4 v[4:5], off
	v_lshl_add_u64 v[4:5], v[2:3], 0, s[12:13]
	s_add_i32 m0, s66, 0x16000
	v_mov_b32_e32 v161, v163
	global_load_lds_dwordx4 v[4:5], off
	v_lshl_add_u64 v[4:5], s[20:21], 0, v[160:161]
	s_mov_b32 m0, s66
	s_add_i32 s67, s66, 0x2000
	global_load_lds_dwordx4 v160, s[20:21]
	v_lshl_add_u64 v[8:9], v[4:5], 0, s[8:9]
	s_mov_b32 m0, s67
	s_add_i32 s68, s66, 0x4000
	global_load_lds_dwordx4 v[8:9], off
	v_lshl_add_u64 v[8:9], v[4:5], 0, s[10:11]
	s_mov_b32 m0, s68
	s_add_i32 s69, s66, 0x6000
	global_load_lds_dwordx4 v[8:9], off
	v_lshl_add_u64 v[8:9], v[4:5], 0, s[12:13]
	s_mov_b32 m0, s69
	v_writelane_b32 v254, s82, 18
	global_load_lds_dwordx4 v[8:9], off
	s_nop 0
	v_writelane_b32 v254, s83, 19
	s_cmp_eq_u32 s2, 1
	s_mov_b32 s96, s53
	s_mov_b32 s53, s81
	v_writelane_b32 v254, s78, 36
	s_cselect_b64 s[14:15], -1, 0
	s_cmp_lg_u32 s2, 1
	s_mov_b32 s23, 0
	v_writelane_b32 v254, s79, 37
	s_cbranch_scc1 .LBB0_1141
	s_barrier

; __device__ __forceinline__ f32x4 ld_nt(const float* p) { return __builtin_nontemporal_load((const f32x4*)p); }
; __device__ __forceinline__ u32x4 pack8h(const f32x4 v0, const f32x4 v1) { u32x4 w; w.x = pk_h16(v0[0], v0[1]); w.y = pk_h16(v0[2], v0[3]); w.z = pk_h16(v1[0], v1[1]); w.w = pk_h16(v1[2], v1[3]); return w; }
;     __device__ __forceinline__ void operator()(AccRef acc, const Unit& u, int wr, int wc, int fr, int fq) const {
;     ...
;                         for (int n = 0; n < 2; ++n) xv[mm][bj][n] = ld_nt(x + (size_t)(row0 + ai * HALF + (mp * 2 + mm) * 16) * D + col0 + bj * HALF + n * 4);
;                 __builtin_amdgcn_sched_barrier(0);
; #pragma unroll
;                 for (int mm = 0; mm < 2; ++mm) { const int m = mp * 2 + mm; const int row = row0 + ai * HALF + m * 16; const size_t o = (size_t)row * D + col0; float ss = 0.f;
; #pragma unroll
;                     for (int bj = 0; bj < 2; ++bj) { const f32x4 r0 = xv[mm][bj][0] + gv[bj][0] * acc[ai][bj][m][0], r1 = xv[mm][bj][1] + gv[bj][1] * acc[ai][bj][m][1];
;                         *(u32x4*)(xo + o + bj * HALF) = pack8h(r0, r1);
;                         ss += ((r0[0] * r0[0] + r0[1] * r0[1]) + (r0[2] * r0[2] + r0[3] * r0[3])) + ((r1[0] * r1[0] + r1[1] * r1[1]) + (r1[2] * r1[2] + r1[3] * r1[3])); }
.LBB0_1154:
	v_lshl_add_u32 v172, s58, 8, v178
	v_lshl_or_b32 v170, s22, 8, v180
	v_readlane_b32 s80, v254, 2
	v_readlane_b32 s81, v254, 3
	v_lshlrev_b32_e32 v173, 13, v172
	v_lshlrev_b32_e32 v187, 7, v172
	v_lshlrev_b32_e32 v171, 2, v170
	v_lshl_add_u32 v173, v170, 2, v173
	s_lshl_b32 s18, s22, 2
	s_add_u32 s18, s18, s72
	s_lshl_b32 s18, s18, 2
	s_add_u32 s88, s26, s18
	s_addc_u32 s89, s27, 0
	v_xor_b32_e32 v186, 16, v184
	v_xor_b32_e32 v185, 32, v184
	v_lshrrev_b32_e32 v174, 4, v184
	v_lshlrev_b32_e32 v186, 2, v186
	v_lshlrev_b32_e32 v185, 2, v185
	v_lshl_add_u32 v174, v174, 5, v187
	s_mov_b32 s94, 0x3a000000
	s_mov_b32 s95, 0x358637bd
	s_mov_b64 s[82:83], s[48:49]
	s_lshr_b32 s59, s65, 10
	global_load_dwordx4 v[144:147], v171, s[46:47]
	global_load_dwordx4 v[148:151], v171, s[46:47] offset:16
	global_load_dwordx4 v[152:155], v171, s[46:47] offset:512
	global_load_dwordx4 v[156:159], v171, s[46:47] offset:528
	s_add_u32 s84, s80, 0x20000
	s_addc_u32 s85, s81, 0
	global_load_dwordx4 v[188:191], v173, s[84:85] nt
	global_load_dwordx4 v[192:195], v173, s[84:85] offset:16 nt
	global_load_dwordx4 v[196:199], v173, s[84:85] offset:512 nt
	global_load_dwordx4 v[200:203], v173, s[84:85] offset:528 nt
	s_add_u32 s84, s80, 0x40000
	s_addc_u32 s85, s81, 0
	global_load_dwordx4 v[104:107], v173, s[84:85] nt
	global_load_dwordx4 v[108:111], v173, s[84:85] offset:16 nt
	global_load_dwordx4 v[112:115], v173, s[84:85] offset:512 nt
	global_load_dwordx4 v[120:123], v173, s[84:85] offset:528 nt
	s_waitcnt vmcnt(12)
	v_pk_fma_f32 v[140:141], v[140:141], v[218:219], v[234:235]
	v_pk_fma_f32 v[142:143], v[142:143], v[220:221], v[236:237]
	v_pk_fma_f32 v[136:137], v[136:137], v[222:223], v[238:239]
	v_pk_fma_f32 v[138:139], v[138:139], v[224:225], v[240:241]
	v_pk_fma_f32 v[132:133], v[132:133], v[226:227], v[242:243]
	v_pk_fma_f32 v[134:135], v[134:135], v[228:229], v[244:245]
	v_pk_fma_f32 v[128:129], v[128:129], v[230:231], v[246:247]
	v_pk_fma_f32 v[130:131], v[130:131], v[232:233], v[248:249]
	s_add_u32 s84, s80, 0x60000
	s_addc_u32 s85, s81, 0
	global_load_dwordx4 v[234:237], v173, s[84:85] nt
	global_load_dwordx4 v[238:241], v173, s[84:85] offset:16 nt
	global_load_dwordx4 v[242:245], v173, s[84:85] offset:512 nt
	global_load_dwordx4 v[246:249], v173, s[84:85] offset:528 nt
	v_pk_mul_f32 v[176:177], v[140:141], v[140:141]
	v_pk_fma_f32 v[176:177], v[142:143], v[142:143], v[176:177]
	v_pk_fma_f32 v[176:177], v[136:137], v[136:137], v[176:177]
	v_pk_fma_f32 v[176:177], v[138:139], v[138:139], v[176:177]
	v_pk_fma_f32 v[176:177], v[132:133], v[132:133], v[176:177]
	v_pk_fma_f32 v[176:177], v[134:135], v[134:135], v[176:177]
	v_pk_fma_f32 v[176:177], v[128:129], v[128:129], v[176:177]
	v_pk_fma_f32 v[176:177], v[130:131], v[130:131], v[176:177]
	v_add_f32_e32 v204, v176, v177
	s_waitcnt vmcnt(8)
	v_pk_fma_f32 v[124:125], v[124:125], v[218:219], v[188:189]
	v_pk_fma_f32 v[126:127], v[126:127], v[220:221], v[190:191]
	v_pk_fma_f32 v[116:117], v[116:117], v[222:223], v[192:193]
	v_pk_fma_f32 v[118:119], v[118:119], v[224:225], v[194:195]
	v_pk_fma_f32 v[100:101], v[100:101], v[226:227], v[196:197]
	v_pk_fma_f32 v[102:103], v[102:103], v[228:229], v[198:199]
	v_pk_fma_f32 v[96:97], v[96:97], v[230:231], v[200:201]
	v_pk_fma_f32 v[98:99], v[98:99], v[232:233], v[202:203]
	s_add_u32 s84, s80, 0x100000
	s_addc_u32 s85, s81, 0
	global_load_dwordx4 v[188:191], v173, s[84:85] nt
	global_load_dwordx4 v[192:195], v173, s[84:85] offset:16 nt
	global_load_dwordx4 v[196:199], v173, s[84:85] offset:512 nt
	global_load_dwordx4 v[200:203], v173, s[84:85] offset:528 nt
	v_pk_mul_f32 v[176:177], v[124:125], v[124:125]
	v_pk_fma_f32 v[176:177], v[126:127], v[126:127], v[176:177]
	v_pk_fma_f32 v[176:177], v[116:117], v[116:117], v[176:177]
	v_pk_fma_f32 v[176:177], v[118:119], v[118:119], v[176:177]
	v_pk_fma_f32 v[176:177], v[100:101], v[100:101], v[176:177]
	v_pk_fma_f32 v[176:177], v[102:103], v[102:103], v[176:177]
	v_pk_fma_f32 v[176:177], v[96:97], v[96:97], v[176:177]
	v_pk_fma_f32 v[176:177], v[98:99], v[98:99], v[176:177]
	v_add_f32_e32 v205, v176, v177
	s_waitcnt vmcnt(8)
	v_pk_fma_f32 v[92:93], v[92:93], v[218:219], v[104:105]
	v_pk_fma_f32 v[94:95], v[94:95], v[220:221], v[106:107]
	v_pk_fma_f32 v[88:89], v[88:89], v[222:223], v[108:109]
	v_pk_fma_f32 v[90:91], v[90:91], v[224:225], v[110:111]
	v_pk_fma_f32 v[84:85], v[84:85], v[226:227], v[112:113]
	v_pk_fma_f32 v[86:87], v[86:87], v[228:229], v[114:115]
	v_pk_fma_f32 v[80:81], v[80:81], v[230:231], v[120:121]
	v_pk_fma_f32 v[82:83], v[82:83], v[232:233], v[122:123]
	s_add_u32 s84, s80, 0x120000
	s_addc_u32 s85, s81, 0
	global_load_dwordx4 v[104:107], v173, s[84:85] nt
	global_load_dwordx4 v[108:111], v173, s[84:85] offset:16 nt
	global_load_dwordx4 v[112:115], v173, s[84:85] offset:512 nt
	global_load_dwordx4 v[120:123], v173, s[84:85] offset:528 nt
	v_pk_mul_f32 v[176:177], v[92:93], v[92:93]
	v_pk_fma_f32 v[176:177], v[94:95], v[94:95], v[176:177]
	v_pk_fma_f32 v[176:177], v[88:89], v[88:89], v[176:177]
	v_pk_fma_f32 v[176:177], v[90:91], v[90:91], v[176:177]
	v_pk_fma_f32 v[176:177], v[84:85], v[84:85], v[176:177]
	v_pk_fma_f32 v[176:177], v[86:87], v[86:87], v[176:177]
	v_pk_fma_f32 v[176:177], v[80:81], v[80:81], v[176:177]
	v_pk_fma_f32 v[176:177], v[82:83], v[82:83], v[176:177]
	v_add_f32_e32 v206, v176, v177
	s_waitcnt vmcnt(8)
; __device__ __forceinline__ u32x4 pack8h(const f32x4 v0, const f32x4 v1) { u32x4 w; w.x = pk_h16(v0[0], v0[1]); w.y = pk_h16(v0[2], v0[3]); w.z = pk_h16(v1[0], v1[1]); w.w = pk_h16(v1[2], v1[3]); return w; }
;     __device__ __forceinline__ void operator()(AccRef acc, const Unit& u, int wr, int wc, int fr, int fq) const {
;     ...
;                 for (int mm = 0; mm < 2; ++mm) { const int m = mp * 2 + mm; const int row = row0 + ai * HALF + m * 16; const size_t o = (size_t)row * D + col0; float ss = 0.f;
; #pragma unroll
;                     for (int bj = 0; bj < 2; ++bj) { const f32x4 r0 = xv[mm][bj][0] + gv[bj][0] * acc[ai][bj][m][0], r1 = xv[mm][bj][1] + gv[bj][1] * acc[ai][bj][m][1];
;                         *(u32x4*)(xo + o + bj * HALF) = pack8h(r0, r1);
;                         ss += ((r0[0] * r0[0] + r0[1] * r0[1]) + (r0[2] * r0[2] + r0[3] * r0[3])) + ((r1[0] * r1[0] + r1[1] * r1[1]) + (r1[2] * r1[2] + r1[3] * r1[3])); }
;                     ss += __shfl_xor(ss, 16); ss += __shfl_xor(ss, 32);
;                     if (fq == 0) rowss[(size_t)row * 32 + u.pn * 4 + wc] = ss; } }
	v_pk_fma_f32 v[76:77], v[76:77], v[218:219], v[234:235]
	v_pk_fma_f32 v[78:79], v[78:79], v[220:221], v[236:237]
	v_pk_fma_f32 v[72:73], v[72:73], v[222:223], v[238:239]
	v_pk_fma_f32 v[74:75], v[74:75], v[224:225], v[240:241]
	v_pk_fma_f32 v[68:69], v[68:69], v[226:227], v[242:243]
	v_pk_fma_f32 v[70:71], v[70:71], v[228:229], v[244:245]
	v_pk_fma_f32 v[64:65], v[64:65], v[230:231], v[246:247]
	v_pk_fma_f32 v[66:67], v[66:67], v[232:233], v[248:249]
	s_add_u32 s84, s80, 0x140000
	s_addc_u32 s85, s81, 0
	global_load_dwordx4 v[234:237], v173, s[84:85] nt
	global_load_dwordx4 v[238:241], v173, s[84:85] offset:16 nt
	global_load_dwordx4 v[242:245], v173, s[84:85] offset:512 nt
	global_load_dwordx4 v[246:249], v173, s[84:85] offset:528 nt
	v_pk_mul_f32 v[176:177], v[76:77], v[76:77]
	v_pk_fma_f32 v[176:177], v[78:79], v[78:79], v[176:177]
	v_pk_fma_f32 v[176:177], v[72:73], v[72:73], v[176:177]
	v_pk_fma_f32 v[176:177], v[74:75], v[74:75], v[176:177]
	v_pk_fma_f32 v[176:177], v[68:69], v[68:69], v[176:177]
	v_pk_fma_f32 v[176:177], v[70:71], v[70:71], v[176:177]
	v_pk_fma_f32 v[176:177], v[64:65], v[64:65], v[176:177]
	v_pk_fma_f32 v[176:177], v[66:67], v[66:67], v[176:177]
	v_add_f32_e32 v207, v176, v177
	ds_bpermute_b32 v214, v186, v204
	ds_bpermute_b32 v215, v186, v205
	ds_bpermute_b32 v216, v186, v206
	ds_bpermute_b32 v217, v186, v207
	s_waitcnt lgkmcnt(0)
	v_pk_add_f32 v[204:205], v[204:205], v[214:215]
	v_pk_add_f32 v[206:207], v[206:207], v[216:217]
	ds_bpermute_b32 v214, v185, v204
	ds_bpermute_b32 v215, v185, v205
	ds_bpermute_b32 v216, v185, v206
	ds_bpermute_b32 v217, v185, v207
	s_waitcnt lgkmcnt(0)
	v_pk_add_f32 v[204:205], v[204:205], v[214:215]
	v_pk_add_f32 v[206:207], v[206:207], v[216:217]
	s_and_saveexec_b64 s[20:21], s[2:3]
	s_mov_b64 s[90:91], s[88:89]
	global_store_dword v187, v204, s[90:91] sc0 sc1
	s_add_u32 s90, s88, 0x800
	s_addc_u32 s91, s89, 0
	global_store_dword v187, v205, s[90:91] sc0 sc1
	s_add_u32 s90, s88, 0x1000
	s_addc_u32 s91, s89, 0
	global_store_dword v187, v206, s[90:91] sc0 sc1
	s_add_u32 s90, s88, 0x1800
	s_addc_u32 s91, s89, 0
	global_store_dword v187, v207, s[90:91] sc0 sc1
	s_or_b64 exec, exec, s[20:21]
	s_waitcnt vmcnt(12)
	v_pk_fma_f32 v[60:61], v[60:61], v[218:219], v[188:189]
	v_pk_fma_f32 v[62:63], v[62:63], v[220:221], v[190:191]
	v_pk_fma_f32 v[56:57], v[56:57], v[222:223], v[192:193]
	v_pk_fma_f32 v[58:59], v[58:59], v[224:225], v[194:195]
	v_pk_fma_f32 v[52:53], v[52:53], v[226:227], v[196:197]
	v_pk_fma_f32 v[54:55], v[54:55], v[228:229], v[198:199]
	v_pk_fma_f32 v[48:49], v[48:49], v[230:231], v[200:201]
	v_pk_fma_f32 v[50:51], v[50:51], v[232:233], v[202:203]
	s_add_u32 s84, s80, 0x160000
	s_addc_u32 s85, s81, 0
	global_load_dwordx4 v[188:191], v173, s[84:85] nt
	global_load_dwordx4 v[192:195], v173, s[84:85] offset:16 nt
	global_load_dwordx4 v[196:199], v173, s[84:85] offset:512 nt
	global_load_dwordx4 v[200:203], v173, s[84:85] offset:528 nt
	v_pk_mul_f32 v[176:177], v[60:61], v[60:61]
	v_pk_fma_f32 v[176:177], v[62:63], v[62:63], v[176:177]
	v_pk_fma_f32 v[176:177], v[56:57], v[56:57], v[176:177]
	v_pk_fma_f32 v[176:177], v[58:59], v[58:59], v[176:177]
	v_pk_fma_f32 v[176:177], v[52:53], v[52:53], v[176:177]
	v_pk_fma_f32 v[176:177], v[54:55], v[54:55], v[176:177]
	v_pk_fma_f32 v[176:177], v[48:49], v[48:49], v[176:177]
	v_pk_fma_f32 v[176:177], v[50:51], v[50:51], v[176:177]
	v_add_f32_e32 v208, v176, v177
	s_waitcnt vmcnt(12)
	v_pk_fma_f32 v[44:45], v[44:45], v[218:219], v[104:105]
	v_pk_fma_f32 v[46:47], v[46:47], v[220:221], v[106:107]
	v_pk_fma_f32 v[40:41], v[40:41], v[222:223], v[108:109]
	v_pk_fma_f32 v[42:43], v[42:43], v[224:225], v[110:111]
	v_pk_fma_f32 v[36:37], v[36:37], v[226:227], v[112:113]
	v_pk_fma_f32 v[38:39], v[38:39], v[228:229], v[114:115]
	v_pk_fma_f32 v[32:33], v[32:33], v[230:231], v[120:121]
	v_pk_fma_f32 v[34:35], v[34:35], v[232:233], v[122:123]
	v_pk_mul_f32 v[176:177], v[44:45], v[44:45]
	v_pk_fma_f32 v[176:177], v[46:47], v[46:47], v[176:177]
	v_pk_fma_f32 v[176:177], v[40:41], v[40:41], v[176:177]
	v_pk_fma_f32 v[176:177], v[42:43], v[42:43], v[176:177]
	v_pk_fma_f32 v[176:177], v[36:37], v[36:37], v[176:177]
	v_pk_fma_f32 v[176:177], v[38:39], v[38:39], v[176:177]
	v_pk_fma_f32 v[176:177], v[32:33], v[32:33], v[176:177]
	v_pk_fma_f32 v[176:177], v[34:35], v[34:35], v[176:177]
	v_add_f32_e32 v209, v176, v177
	s_waitcnt vmcnt(4)
	v_pk_fma_f32 v[28:29], v[28:29], v[218:219], v[234:235]
	v_pk_fma_f32 v[30:31], v[30:31], v[220:221], v[236:237]
	v_pk_fma_f32 v[24:25], v[24:25], v[222:223], v[238:239]
	v_pk_fma_f32 v[26:27], v[26:27], v[224:225], v[240:241]
	v_pk_fma_f32 v[20:21], v[20:21], v[226:227], v[242:243]
	v_pk_fma_f32 v[22:23], v[22:23], v[228:229], v[244:245]
	v_pk_fma_f32 v[16:17], v[16:17], v[230:231], v[246:247]
	v_pk_fma_f32 v[18:19], v[18:19], v[232:233], v[248:249]
	v_pk_mul_f32 v[176:177], v[28:29], v[28:29]
	v_pk_fma_f32 v[176:177], v[30:31], v[30:31], v[176:177]
	v_pk_fma_f32 v[176:177], v[24:25], v[24:25], v[176:177]
	v_pk_fma_f32 v[176:177], v[26:27], v[26:27], v[176:177]
	v_pk_fma_f32 v[176:177], v[20:21], v[20:21], v[176:177]
	v_pk_fma_f32 v[176:177], v[22:23], v[22:23], v[176:177]
	v_pk_fma_f32 v[176:177], v[16:17], v[16:17], v[176:177]
	v_pk_fma_f32 v[176:177], v[18:19], v[18:19], v[176:177]
	v_add_f32_e32 v210, v176, v177
	s_barrier
	s_cmp_lg_u32 s59, 0
	s_cbranch_scc1 .Lepi_a1
	s_lshl_b32 s18, s58, 6
	s_add_u32 s18, s18, 0xc000
	s_mov_b64 exec, 1
	v_mov_b32_e32 v175, s18
	v_mov_b32_e32 v255, 1
	global_atomic_add v175, v255, s[50:51]
	s_mov_b64 exec, -1
.Lepi_a1:
	s_waitcnt vmcnt(0)
	v_pk_fma_f32 v[12:13], v[12:13], v[218:219], v[188:189]
	v_pk_fma_f32 v[14:15], v[14:15], v[220:221], v[190:191]
	v_pk_fma_f32 v[8:9], v[8:9], v[222:223], v[192:193]
	v_pk_fma_f32 v[10:11], v[10:11], v[224:225], v[194:195]
	v_pk_fma_f32 v[4:5], v[4:5], v[226:227], v[196:197]
	v_pk_fma_f32 v[6:7], v[6:7], v[228:229], v[198:199]
	v_pk_fma_f32 v[0:1], v[0:1], v[230:231], v[200:201]
	v_pk_fma_f32 v[2:3], v[2:3], v[232:233], v[202:203]
	v_pk_mul_f32 v[176:177], v[12:13], v[12:13]
	v_pk_fma_f32 v[176:177], v[14:15], v[14:15], v[176:177]
	v_pk_fma_f32 v[176:177], v[8:9], v[8:9], v[176:177]
	v_pk_fma_f32 v[176:177], v[10:11], v[10:11], v[176:177]
	v_pk_fma_f32 v[176:177], v[4:5], v[4:5], v[176:177]
	v_pk_fma_f32 v[176:177], v[6:7], v[6:7], v[176:177]
	v_pk_fma_f32 v[176:177], v[0:1], v[0:1], v[176:177]
	v_pk_fma_f32 v[176:177], v[2:3], v[2:3], v[176:177]
	v_add_f32_e32 v211, v176, v177
	s_cmp_lg_u32 s59, 0
	s_cbranch_scc1 .Lepi_b1
	s_waitcnt vmcnt(0)
	s_lshl_b32 s18, s58, 6
	s_add_u32 s18, s18, 0xc000
	s_mov_b64 exec, 1
	v_mov_b32_e32 v175, s18
	s_mov_b32 vcc_lo, 0

;     __device__ __forceinline__ void operator()(AccRef acc, const Unit& u, int wr, int wc, int fr, int fq) const {
;     ...
;                     ss += __shfl_xor(ss, 16); ss += __shfl_xor(ss, 32);
;                     if (fq == 0) rowss[(size_t)row * 32 + u.pn * 4 + wc] = ss; } }
; __device__ __forceinline__ void final_rows(int gw, int lane, const f16* xo, float* out, const float* fg, const float* rowss) {
;     ...
;         for (int rr = 0; rr < 4; ++rr) { part[rr] = lane < 32 ? rowss[(size_t)(r0 + rr) * 32 + lane] : 0.f;
; #pragma unroll
;             for (int j = 0; j < 4; ++j) v[rr][j] = *(const u32x4*)(xo + (size_t)(r0 + rr) * D + 512 * j + 8 * lane); }
;         __builtin_amdgcn_sched_barrier(0);
; #pragma unroll
;         for (int rr = 0; rr < 4; ++rr) { const float rstd = rsqrtf(wave_sum(part[rr]) * (1.f / D) + EPS); float* rp = out + (size_t)(r0 + rr) * D + 8 * lane;
.Lepi_b1:
	ds_bpermute_b32 v214, v186, v208
	ds_bpermute_b32 v215, v186, v209
	ds_bpermute_b32 v216, v186, v210
	ds_bpermute_b32 v217, v186, v211
	s_waitcnt lgkmcnt(0)
	v_pk_add_f32 v[208:209], v[208:209], v[214:215]
	v_pk_add_f32 v[210:211], v[210:211], v[216:217]
	ds_bpermute_b32 v214, v185, v208
	ds_bpermute_b32 v215, v185, v209
	ds_bpermute_b32 v216, v185, v210
	ds_bpermute_b32 v217, v185, v211
	s_waitcnt lgkmcnt(0)
	v_pk_add_f32 v[208:209], v[208:209], v[214:215]
	v_pk_add_f32 v[210:211], v[210:211], v[216:217]
	s_and_saveexec_b64 s[20:21], s[2:3]
	s_add_u32 s90, s88, 0x4000
	s_addc_u32 s91, s89, 0
	global_store_dword v187, v208, s[90:91] sc0 sc1
	s_add_u32 s90, s88, 0x4800
	s_addc_u32 s91, s89, 0
	global_store_dword v187, v209, s[90:91] sc0 sc1
	s_add_u32 s90, s88, 0x5000
	s_addc_u32 s91, s89, 0
	global_store_dword v187, v210, s[90:91] sc0 sc1
	s_add_u32 s90, s88, 0x5800
	s_addc_u32 s91, s89, 0
	global_store_dword v187, v211, s[90:91] sc0 sc1
	s_or_b64 exec, exec, s[20:21]
	s_barrier
	s_mov_b64 s[90:91], s[26:27]
	global_load_dwordx4 v[188:191], v174, s[90:91]
	global_load_dwordx4 v[192:195], v174, s[90:91] offset:16
	s_add_u32 s90, s26, 0x800
	s_addc_u32 s91, s27, 0
	global_load_dwordx4 v[196:199], v174, s[90:91]
	global_load_dwordx4 v[200:203], v174, s[90:91] offset:16
	s_add_u32 s90, s26, 0x1000
	s_addc_u32 s91, s27, 0
	global_load_dwordx4 v[104:107], v174, s[90:91]
	global_load_dwordx4 v[108:111], v174, s[90:91] offset:16
	s_add_u32 s90, s26, 0x1800
	s_addc_u32 s91, s27, 0
	global_load_dwordx4 v[112:115], v174, s[90:91]
	global_load_dwordx4 v[120:123], v174, s[90:91] offset:16
	s_waitcnt vmcnt(8)
	s_barrier
	s_cmp_lg_u32 s59, 0
	s_cbranch_scc1 .Lepi_c1
	s_lshl_b32 s18, s58, 6
	s_add_u32 s18, s18, 0xc020
	s_mov_b64 exec, 1
	v_mov_b32_e32 v175, s18
	v_mov_b32_e32 v255, 1
	global_atomic_add v175, v255, s[50:51]
	s_mov_b64 exec, -1
.Lepi_c1:
	s_waitcnt vmcnt(0)
	v_pk_add_f32 v[188:189], v[188:189], v[190:191]
	v_pk_add_f32 v[192:193], v[192:193], v[194:195]
	v_pk_add_f32 v[188:189], v[188:189], v[192:193]
	v_add_f32_e32 v188, v188, v189
	v_pk_add_f32 v[196:197], v[196:197], v[198:199]
	v_pk_add_f32 v[200:201], v[200:201], v[202:203]
	v_pk_add_f32 v[196:197], v[196:197], v[200:201]
	v_add_f32_e32 v196, v196, v197
	v_pk_add_f32 v[104:105], v[104:105], v[106:107]
	v_pk_add_f32 v[108:109], v[108:109], v[110:111]
	v_pk_add_f32 v[104:105], v[104:105], v[108:109]
	v_add_f32_e32 v104, v104, v105
	v_pk_add_f32 v[112:113], v[112:113], v[114:115]
	v_pk_add_f32 v[120:121], v[120:121], v[122:123]
	v_pk_add_f32 v[112:113], v[112:113], v[120:121]
	v_add_f32_e32 v112, v112, v113
	ds_bpermute_b32 v214, v186, v188
	ds_bpermute_b32 v215, v186, v196
	ds_bpermute_b32 v216, v186, v104
	ds_bpermute_b32 v217, v186, v112
	s_waitcnt lgkmcnt(0)
	v_add_f32_e32 v188, v188, v214
	v_add_f32_e32 v196, v196, v215
	v_add_f32_e32 v104, v104, v216
	v_add_f32_e32 v112, v112, v217
	ds_bpermute_b32 v214, v185, v188
	ds_bpermute_b32 v215, v185, v196
	ds_bpermute_b32 v216, v185, v104
	ds_bpermute_b32 v217, v185, v112
	s_waitcnt lgkmcnt(0)
	v_add_f32_e32 v188, v188, v214
	v_add_f32_e32 v196, v196, v215
	v_add_f32_e32 v104, v104, v216
	v_add_f32_e32 v112, v112, v217
	v_mov_b32_e32 v214, s95
	v_mov_b32_e32 v215, s95
	v_mov_b32_e32 v216, s95
	v_mov_b32_e32 v217, s95
	v_fmac_f32_e32 v214, s94, v188
	v_fmac_f32_e32 v215, s94, v196
	v_fmac_f32_e32 v216, s94, v104
	v_fmac_f32_e32 v217, s94, v112
	v_rsq_f32_e32 v204, v214
	v_rsq_f32_e32 v206, v215
	v_rsq_f32_e32 v208, v216
	v_rsq_f32_e32 v210, v217
	s_nop 1
	s_cmp_lg_u32 s59, 0
	s_cbranch_scc1 .Lepi_d1
	s_waitcnt vmcnt(0)
	s_lshl_b32 s18, s58, 6
	s_add_u32 s18, s18, 0xc020
	s_mov_b64 exec, 1
	v_mov_b32_e32 v175, s18
	s_mov_b32 vcc_lo, 0

; __device__ __forceinline__ void unpack8h(const u32x4 w, f32x4& v0, f32x4& v1) { v0 = (f32x4){h16lo(w.x), h16hi(w.x), h16lo(w.y), h16hi(w.y)}; v1 = (f32x4){h16lo(w.z), h16hi(w.z), h16lo(w.w), h16hi(w.w)}; }
; __device__ __forceinline__ void final_rows(int gw, int lane, const f16* xo, float* out, const float* fg, const float* rowss) {
;     ...
;         for (int rr = 0; rr < 4; ++rr) { const float rstd = rsqrtf(wave_sum(part[rr]) * (1.f / D) + EPS); float* rp = out + (size_t)(r0 + rr) * D + 8 * lane;
; #pragma unroll
;             for (int j = 0; j < 4; ++j) { f32x4 a0, a1; unpack8h(v[rr][j], a0, a1); *(f32x4*)(rp + 512 * j) = a0 * rstd * g4[j][0]; *(f32x4*)(rp + 512 * j + 4) = a1 * rstd * g4[j][1]; } }
.Lepi_d1:
	s_barrier
	s_add_u32 s90, s26, 0x4000
	s_addc_u32 s91, s27, 0
	global_load_dwordx4 v[188:191], v174, s[90:91]
	global_load_dwordx4 v[192:195], v174, s[90:91] offset:16
	s_add_u32 s90, s26, 0x4800
	s_addc_u32 s91, s27, 0
	global_load_dwordx4 v[196:199], v174, s[90:91]
	global_load_dwordx4 v[200:203], v174, s[90:91] offset:16
	s_add_u32 s90, s26, 0x5000
	s_addc_u32 s91, s27, 0
	global_load_dwordx4 v[104:107], v174, s[90:91]
	global_load_dwordx4 v[108:111], v174, s[90:91] offset:16
	s_add_u32 s90, s26, 0x5800
	s_addc_u32 s91, s27, 0
	global_load_dwordx4 v[112:115], v174, s[90:91]
	global_load_dwordx4 v[120:123], v174, s[90:91] offset:16
	s_mov_b64 s[86:87], s[82:83]
	v_pk_mul_f32 v[140:141], v[140:141], v[204:205] op_sel_hi:[1,0]
	v_pk_mul_f32 v[142:143], v[142:143], v[204:205] op_sel_hi:[1,0]
	v_pk_mul_f32 v[140:141], v[140:141], v[144:145]
	v_pk_mul_f32 v[142:143], v[142:143], v[146:147]
	v_pk_mul_f32 v[136:137], v[136:137], v[204:205] op_sel_hi:[1,0]
	v_pk_mul_f32 v[138:139], v[138:139], v[204:205] op_sel_hi:[1,0]
	v_pk_mul_f32 v[136:137], v[136:137], v[148:149]
	v_pk_mul_f32 v[138:139], v[138:139], v[150:151]
	v_pk_mul_f32 v[132:133], v[132:133], v[204:205] op_sel_hi:[1,0]
	v_pk_mul_f32 v[134:135], v[134:135], v[204:205] op_sel_hi:[1,0]
	v_pk_mul_f32 v[132:133], v[132:133], v[152:153]
	v_pk_mul_f32 v[134:135], v[134:135], v[154:155]
	v_pk_mul_f32 v[128:129], v[128:129], v[204:205] op_sel_hi:[1,0]
	v_pk_mul_f32 v[130:131], v[130:131], v[204:205] op_sel_hi:[1,0]
	v_pk_mul_f32 v[128:129], v[128:129], v[156:157]
	v_pk_mul_f32 v[130:131], v[130:131], v[158:159]
	global_store_dwordx4 v173, v[140:143], s[86:87]
	global_store_dwordx4 v173, v[136:139], s[86:87] offset:16
	global_store_dwordx4 v173, v[132:135], s[86:87] offset:512
	global_store_dwordx4 v173, v[128:131], s[86:87] offset:528
	s_add_u32 s86, s82, 0x20000
	s_addc_u32 s87, s83, 0
	v_pk_mul_f32 v[124:125], v[124:125], v[206:207] op_sel_hi:[1,0]
	v_pk_mul_f32 v[126:127], v[126:127], v[206:207] op_sel_hi:[1,0]
	v_pk_mul_f32 v[124:125], v[124:125], v[144:145]
	v_pk_mul_f32 v[126:127], v[126:127], v[146:147]
	v_pk_mul_f32 v[116:117], v[116:117], v[206:207] op_sel_hi:[1,0]
	v_pk_mul_f32 v[118:119], v[118:119], v[206:207] op_sel_hi:[1,0]
	v_pk_mul_f32 v[116:117], v[116:117], v[148:149]
	v_pk_mul_f32 v[118:119], v[118:119], v[150:151]
	v_pk_mul_f32 v[100:101], v[100:101], v[206:207] op_sel_hi:[1,0]
	v_pk_mul_f32 v[102:103], v[102:103], v[206:207] op_sel_hi:[1,0]
	v_pk_mul_f32 v[100:101], v[100:101], v[152:153]
	v_pk_mul_f32 v[102:103], v[102:103], v[154:155]
	v_pk_mul_f32 v[96:97], v[96:97], v[206:207] op_sel_hi:[1,0]
	v_pk_mul_f32 v[98:99], v[98:99], v[206:207] op_sel_hi:[1,0]
	v_pk_mul_f32 v[96:97], v[96:97], v[156:157]
	v_pk_mul_f32 v[98:99], v[98:99], v[158:159]
	global_store_dwordx4 v173, v[124:127], s[86:87]
	global_store_dwordx4 v173, v[116:119], s[86:87] offset:16
	global_store_dwordx4 v173, v[100:103], s[86:87] offset:512
	global_store_dwordx4 v173, v[96:99], s[86:87] offset:528
	s_add_u32 s86, s82, 0x40000
	s_addc_u32 s87, s83, 0
	v_pk_mul_f32 v[92:93], v[92:93], v[208:209] op_sel_hi:[1,0]
	v_pk_mul_f32 v[94:95], v[94:95], v[208:209] op_sel_hi:[1,0]
	v_pk_mul_f32 v[92:93], v[92:93], v[144:145]
	v_pk_mul_f32 v[94:95], v[94:95], v[146:147]
	v_pk_mul_f32 v[88:89], v[88:89], v[208:209] op_sel_hi:[1,0]
	v_pk_mul_f32 v[90:91], v[90:91], v[208:209] op_sel_hi:[1,0]
	v_pk_mul_f32 v[88:89], v[88:89], v[148:149]
	v_pk_mul_f32 v[90:91], v[90:91], v[150:151]
	v_pk_mul_f32 v[84:85], v[84:85], v[208:209] op_sel_hi:[1,0]
	v_pk_mul_f32 v[86:87], v[86:87], v[208:209] op_sel_hi:[1,0]
	v_pk_mul_f32 v[84:85], v[84:85], v[152:153]
	v_pk_mul_f32 v[86:87], v[86:87], v[154:155]
	v_pk_mul_f32 v[80:81], v[80:81], v[208:209] op_sel_hi:[1,0]
	v_pk_mul_f32 v[82:83], v[82:83], v[208:209] op_sel_hi:[1,0]
	v_pk_mul_f32 v[80:81], v[80:81], v[156:157]
	v_pk_mul_f32 v[82:83], v[82:83], v[158:159]
	global_store_dwordx4 v173, v[92:95], s[86:87]
	global_store_dwordx4 v173, v[88:91], s[86:87] offset:16
	global_store_dwordx4 v173, v[84:87], s[86:87] offset:512
	global_store_dwordx4 v173, v[80:83], s[86:87] offset:528
	s_add_u32 s86, s82, 0x60000
	s_addc_u32 s87, s83, 0
	v_pk_mul_f32 v[76:77], v[76:77], v[210:211] op_sel_hi:[1,0]
	v_pk_mul_f32 v[78:79], v[78:79], v[210:211] op_sel_hi:[1,0]
	v_pk_mul_f32 v[76:77], v[76:77], v[144:145]
	v_pk_mul_f32 v[78:79], v[78:79], v[146:147]
	v_pk_mul_f32 v[72:73], v[72:73], v[210:211] op_sel_hi:[1,0]
	v_pk_mul_f32 v[74:75], v[74:75], v[210:211] op_sel_hi:[1,0]
	v_pk_mul_f32 v[72:73], v[72:73], v[148:149]
	v_pk_mul_f32 v[74:75], v[74:75], v[150:151]
	v_pk_mul_f32 v[68:69], v[68:69], v[210:211] op_sel_hi:[1,0]
	v_pk_mul_f32 v[70:71], v[70:71], v[210:211] op_sel_hi:[1,0]
	v_pk_mul_f32 v[68:69], v[68:69], v[152:153]
	v_pk_mul_f32 v[70:71], v[70:71], v[154:155]
	v_pk_mul_f32 v[64:65], v[64:65], v[210:211] op_sel_hi:[1,0]
	v_pk_mul_f32 v[66:67], v[66:67], v[210:211] op_sel_hi:[1,0]
	v_pk_mul_f32 v[64:65], v[64:65], v[156:157]
	v_pk_mul_f32 v[66:67], v[66:67], v[158:159]
	global_store_dwordx4 v173, v[76:79], s[86:87]
	global_store_dwordx4 v173, v[72:75], s[86:87] offset:16
	global_store_dwordx4 v173, v[68:71], s[86:87] offset:512
	global_store_dwordx4 v173, v[64:67], s[86:87] offset:528
	s_waitcnt vmcnt(16)
; __device__ __forceinline__ f32x4 ld_nt(const float* p) { return __builtin_nontemporal_load((const f32x4*)p); }
; __device__ __forceinline__ u32x4 pack8h(const f32x4 v0, const f32x4 v1) { u32x4 w; w.x = pk_h16(v0[0], v0[1]); w.y = pk_h16(v0[2], v0[3]); w.z = pk_h16(v1[0], v1[1]); w.w = pk_h16(v1[2], v1[3]); return w; }
;     __device__ __forceinline__ void operator()(AccRef acc, const Unit& u, int wr, int wc, int fr, int fq) const {
;     ...
;         const float* gate = mod + (size_t)(u.pm >= 32 ? 1 : 0) * 3 * D + 2 * D + col0;
;         f32x4 gv[2][2];
; #pragma unroll
;         for (int bj = 0; bj < 2; ++bj)
; #pragma unroll
;             for (int n = 0; n < 2; ++n) gv[bj][n] = *(const f32x4*)(gate + bj * HALF + n * 4);
; #pragma unroll
;         for (int ai = 0; ai < 2; ++ai)
; #pragma unroll
;             for (int mp = 0; mp < 2; ++mp) { f32x4 xv[2][2][2];
; #pragma unroll
;                 for (int mm = 0; mm < 2; ++mm)
; #pragma unroll
;                     for (int bj = 0; bj < 2; ++bj)
; #pragma unroll
;                         for (int n = 0; n < 2; ++n) xv[mm][bj][n] = ld_nt(x + (size_t)(row0 + ai * HALF + (mp * 2 + mm) * 16) * D + col0 + bj * HALF + n * 4);
;                 __builtin_amdgcn_sched_barrier(0);
; #pragma unroll
;                 for (int mm = 0; mm < 2; ++mm) { const int m = mp * 2 + mm; const int row = row0 + ai * HALF + m * 16; const size_t o = (size_t)row * D + col0; float ss = 0.f;
; #pragma unroll
;                     for (int bj = 0; bj < 2; ++bj) { const f32x4 r0 = xv[mm][bj][0] + gv[bj][0] * acc[ai][bj][m][0], r1 = xv[mm][bj][1] + gv[bj][1] * acc[ai][bj][m][1];
;                         *(u32x4*)(xo + o + bj * HALF) = pack8h(r0, r1);
;                         ss += ((r0[0] * r0[0] + r0[1] * r0[1]) + (r0[2] * r0[2] + r0[3] * r0[3])) + ((r1[0] * r1[0] + r1[1] * r1[1]) + (r1[2] * r1[2] + r1[3] * r1[3])); }
;                     ss += __shfl_xor(ss, 16); ss += __shfl_xor(ss, 32);
;                     if (fq == 0) rowss[(size_t)row * 32 + u.pn * 4 + wc] = ss; } }
	v_pk_add_f32 v[188:189], v[188:189], v[190:191]
	v_pk_add_f32 v[192:193], v[192:193], v[194:195]
	v_pk_add_f32 v[188:189], v[188:189], v[192:193]
	v_add_f32_e32 v188, v188, v189
	v_pk_add_f32 v[196:197], v[196:197], v[198:199]
	v_pk_add_f32 v[200:201], v[200:201], v[202:203]
	v_pk_add_f32 v[196:197], v[196:197], v[200:201]
	v_add_f32_e32 v196, v196, v197
	v_pk_add_f32 v[104:105], v[104:105], v[106:107]
	v_pk_add_f32 v[108:109], v[108:109], v[110:111]
	v_pk_add_f32 v[104:105], v[104:105], v[108:109]
	v_add_f32_e32 v104, v104, v105
	v_pk_add_f32 v[112:113], v[112:113], v[114:115]
	v_pk_add_f32 v[120:121], v[120:121], v[122:123]
	v_pk_add_f32 v[112:113], v[112:113], v[120:121]
	v_add_f32_e32 v112, v112, v113
	ds_bpermute_b32 v214, v186, v188
	ds_bpermute_b32 v215, v186, v196
	ds_bpermute_b32 v216, v186, v104
	ds_bpermute_b32 v217, v186, v112
	s_waitcnt lgkmcnt(0)
	v_add_f32_e32 v188, v188, v214
	v_add_f32_e32 v196, v196, v215
	v_add_f32_e32 v104, v104, v216
	v_add_f32_e32 v112, v112, v217
	ds_bpermute_b32 v214, v185, v188
	ds_bpermute_b32 v215, v185, v196
	ds_bpermute_b32 v216, v185, v104
	ds_bpermute_b32 v217, v185, v112
	s_waitcnt lgkmcnt(0)
	v_add_f32_e32 v188, v188, v214
	v_add_f32_e32 v196, v196, v215
	v_add_f32_e32 v104, v104, v216
	v_add_f32_e32 v112, v112, v217
	v_mov_b32_e32 v214, s95
	v_mov_b32_e32 v215, s95
	v_mov_b32_e32 v216, s95
	v_mov_b32_e32 v217, s95
	v_fmac_f32_e32 v214, s94, v188
	v_fmac_f32_e32 v215, s94, v196
	v_fmac_f32_e32 v216, s94, v104
	v_fmac_f32_e32 v217, s94, v112
	v_rsq_f32_e32 v204, v214
	v_rsq_f32_e32 v206, v215
	v_rsq_f32_e32 v208, v216
	v_rsq_f32_e32 v210, v217
	s_nop 1
	s_add_u32 s86, s82, 0x100000
	s_addc_u32 s87, s83, 0
	v_pk_mul_f32 v[60:61], v[60:61], v[204:205] op_sel_hi:[1,0]
	v_pk_mul_f32 v[62:63], v[62:63], v[204:205] op_sel_hi:[1,0]
	v_pk_mul_f32 v[60:61], v[60:61], v[144:145]
	v_pk_mul_f32 v[62:63], v[62:63], v[146:147]
	v_pk_mul_f32 v[56:57], v[56:57], v[204:205] op_sel_hi:[1,0]
	v_pk_mul_f32 v[58:59], v[58:59], v[204:205] op_sel_hi:[1,0]
	v_pk_mul_f32 v[56:57], v[56:57], v[148:149]
	v_pk_mul_f32 v[58:59], v[58:59], v[150:151]
	v_pk_mul_f32 v[52:53], v[52:53], v[204:205] op_sel_hi:[1,0]
	v_pk_mul_f32 v[54:55], v[54:55], v[204:205] op_sel_hi:[1,0]
	v_pk_mul_f32 v[52:53], v[52:53], v[152:153]
	v_pk_mul_f32 v[54:55], v[54:55], v[154:155]
	v_pk_mul_f32 v[48:49], v[48:49], v[204:205] op_sel_hi:[1,0]
	v_pk_mul_f32 v[50:51], v[50:51], v[204:205] op_sel_hi:[1,0]
	v_pk_mul_f32 v[48:49], v[48:49], v[156:157]
	v_pk_mul_f32 v[50:51], v[50:51], v[158:159]
	global_store_dwordx4 v173, v[60:63], s[86:87]
	global_store_dwordx4 v173, v[56:59], s[86:87] offset:16
	global_store_dwordx4 v173, v[52:55], s[86:87] offset:512
	global_store_dwordx4 v173, v[48:51], s[86:87] offset:528
	s_add_u32 s86, s82, 0x120000
	s_addc_u32 s87, s83, 0
	v_pk_mul_f32 v[44:45], v[44:45], v[206:207] op_sel_hi:[1,0]
	v_pk_mul_f32 v[46:47], v[46:47], v[206:207] op_sel_hi:[1,0]
	v_pk_mul_f32 v[44:45], v[44:45], v[144:145]
	v_pk_mul_f32 v[46:47], v[46:47], v[146:147]
	v_pk_mul_f32 v[40:41], v[40:41], v[206:207] op_sel_hi:[1,0]
	v_pk_mul_f32 v[42:43], v[42:43], v[206:207] op_sel_hi:[1,0]
	v_pk_mul_f32 v[40:41], v[40:41], v[148:149]
	v_pk_mul_f32 v[42:43], v[42:43], v[150:151]
	v_pk_mul_f32 v[36:37], v[36:37], v[206:207] op_sel_hi:[1,0]
	v_pk_mul_f32 v[38:39], v[38:39], v[206:207] op_sel_hi:[1,0]
	v_pk_mul_f32 v[36:37], v[36:37], v[152:153]
	v_pk_mul_f32 v[38:39], v[38:39], v[154:155]
	v_pk_mul_f32 v[32:33], v[32:33], v[206:207] op_sel_hi:[1,0]
	v_pk_mul_f32 v[34:35], v[34:35], v[206:207] op_sel_hi:[1,0]
	v_pk_mul_f32 v[32:33], v[32:33], v[156:157]
	v_pk_mul_f32 v[34:35], v[34:35], v[158:159]
	global_store_dwordx4 v173, v[44:47], s[86:87]
	global_store_dwordx4 v173, v[40:43], s[86:87] offset:16
	global_store_dwordx4 v173, v[36:39], s[86:87] offset:512
	global_store_dwordx4 v173, v[32:35], s[86:87] offset:528
	s_add_u32 s86, s82, 0x140000
	s_addc_u32 s87, s83, 0
	v_pk_mul_f32 v[28:29], v[28:29], v[208:209] op_sel_hi:[1,0]
	v_pk_mul_f32 v[30:31], v[30:31], v[208:209] op_sel_hi:[1,0]
	v_pk_mul_f32 v[28:29], v[28:29], v[144:145]
	v_pk_mul_f32 v[30:31], v[30:31], v[146:147]
	v_pk_mul_f32 v[24:25], v[24:25], v[208:209] op_sel_hi:[1,0]
	v_pk_mul_f32 v[26:27], v[26:27], v[208:209] op_sel_hi:[1,0]
	v_pk_mul_f32 v[24:25], v[24:25], v[148:149]
	v_pk_mul_f32 v[26:27], v[26:27], v[150:151]
	v_pk_mul_f32 v[20:21], v[20:21], v[208:209] op_sel_hi:[1,0]
	v_pk_mul_f32 v[22:23], v[22:23], v[208:209] op_sel_hi:[1,0]
	v_pk_mul_f32 v[20:21], v[20:21], v[152:153]
	v_pk_mul_f32 v[22:23], v[22:23], v[154:155]
	v_pk_mul_f32 v[16:17], v[16:17], v[208:209] op_sel_hi:[1,0]
	v_pk_mul_f32 v[18:19], v[18:19], v[208:209] op_sel_hi:[1,0]
	v_pk_mul_f32 v[16:17], v[16:17], v[156:157]
	v_pk_mul_f32 v[18:19], v[18:19], v[158:159]
	global_store_dwordx4 v173, v[28:31], s[86:87]
	global_store_dwordx4 v173, v[24:27], s[86:87] offset:16
	global_store_dwordx4 v173, v[20:23], s[86:87] offset:512
	global_store_dwordx4 v173, v[16:19], s[86:87] offset:528
	s_add_u32 s86, s82, 0x160000
	s_addc_u32 s87, s83, 0
	v_pk_mul_f32 v[12:13], v[12:13], v[210:211] op_sel_hi:[1,0]
	v_pk_mul_f32 v[14:15], v[14:15], v[210:211] op_sel_hi:[1,0]
	v_pk_mul_f32 v[12:13], v[12:13], v[144:145]
	v_pk_mul_f32 v[14:15], v[14:15], v[146:147]
	v_pk_mul_f32 v[8:9], v[8:9], v[210:211] op_sel_hi:[1,0]
	v_pk_mul_f32 v[10:11], v[10:11], v[210:211] op_sel_hi:[1,0]
	v_pk_mul_f32 v[8:9], v[8:9], v[148:149]
	v_pk_mul_f32 v[10:11], v[10:11], v[150:151]
	v_pk_mul_f32 v[4:5], v[4:5], v[210:211] op_sel_hi:[1,0]
	v_pk_mul_f32 v[6:7], v[6:7], v[210:211] op_sel_hi:[1,0]
	v_pk_mul_f32 v[4:5], v[4:5], v[152:153]
	v_pk_mul_f32 v[6:7], v[6:7], v[154:155]
	v_pk_mul_f32 v[0:1], v[0:1], v[210:211] op_sel_hi:[1,0]
	v_pk_mul_f32 v[2:3], v[2:3], v[210:211] op_sel_hi:[1,0]
	v_pk_mul_f32 v[0:1], v[0:1], v[156:157]
	v_pk_mul_f32 v[2:3], v[2:3], v[158:159]
	global_store_dwordx4 v173, v[12:15], s[86:87]
	global_store_dwordx4 v173, v[8:11], s[86:87] offset:16
	global_store_dwordx4 v173, v[4:7], s[86:87] offset:512
	global_store_dwordx4 v173, v[0:3], s[86:87] offset:528
	s_and_b64 vcc, exec, s[4:5]
	s_cbranch_vccz .Lepi_nopre
	v_lshl_add_u32 v250, s44, 8, v178
	v_lshl_or_b32 v251, s42, 8, v180
	v_readlane_b32 s98, v254, 2
	v_readlane_b32 s99, v254, 3
	v_lshlrev_b32_e32 v250, 13, v250
	v_lshlrev_b32_e32 v251, 2, v251
	s_cmp_gt_i32 s44, 31
	s_cselect_b32 vcc_lo, 0x6000, 0
	s_add_u32 s100, s50, vcc_lo
	s_addc_u32 s101, s51, 0
	s_add_u32 s100, s100, 0x104000
	s_addc_u32 s101, s101, 0
	v_add_u32_e32 v250, v250, v251
	s_nop 1
	global_load_dwordx4 v[218:221], v251, s[100:101]
	global_load_dwordx4 v[222:225], v251, s[100:101] offset:16
	global_load_dwordx4 v[226:229], v251, s[100:101] offset:512
	global_load_dwordx4 v[230:233], v251, s[100:101] offset:528
	global_load_dwordx4 v[234:237], v250, s[98:99] nt
	global_load_dwordx4 v[238:241], v250, s[98:99] offset:16 nt
	global_load_dwordx4 v[242:245], v250, s[98:99] offset:512 nt
	global_load_dwordx4 v[246:249], v250, s[98:99] offset:528 nt
; #define PG8_BAR __builtin_amdgcn_s_barrier()
; template <class CF, class Epi, class Sched, bool ALIGN_EPI, bool SP2>
; __device__ __forceinline__ void gemm_phase(LAS unsigned char* lds, const char* gA, const char* gB, const Sched& S, const Epi& E, const char* gB2 = nullptr) {
;     ...
;         if constexpr (ALIGN_EPI) { if (wr == 0) PG8_BAR; }
;         E(acc, cur, wr, wc, fr, fq);
;         if (!has_next) break;
; #pragma unroll
;         for (int a = 0; a < 2; ++a)
; #pragma unroll
;             for (int b = 0; b < 2; ++b)
; #pragma unroll
;                 for (int m = 0; m < 4; ++m)
; #pragma unroll
;                     for (int n = 0; n < 2; ++n) acc[a][b][m][n] = (f32x4){0.f, 0.f, 0.f, 0.f};
;         cur = nxt; cA = nA; cB = nB; ++ui;
;         if constexpr (BMODE == 1) cT = gB2 + (size_t)cur.g * KTG + (size_t)cur.pn * 8192 + 14336;
;         if constexpr (ALIGN_EPI) { if (wr == 1) PG8_BAR; }
;     }
.Lepi_nopre:
	s_andn2_b64 vcc, exec, s[4:5]
	s_mov_b64 s[4:5], -1
	s_cbranch_vccnz .LBB0_1143
	s_andn2_b64 vcc, exec, s[14:15]
	s_cbranch_vccnz .LBB0_1142
	s_barrier
	s_branch .LBB0_1142
